# attention: static s_setprio 1 for waves 4-7 during the attention phase (on top of previous)
# baseline (speedup 1.0000x reference)
.LBB0_126:
	v_readlane_b32 s0, v252, 48
	v_readlane_b32 s1, v252, 49
	s_andn2_b64 vcc, exec, s[0:1]
	s_barrier
	s_cbranch_vccnz .LBB0_227
	v_readfirstlane_b32 s32, v200
	s_nop 3
	s_lshr_b32 s32, s32, 8
	s_cmp_eq_u32 s32, 0
	s_cbranch_scc1 .Lprio_skip
	s_setprio 1
.Lprio_skip:
	s_lshl_b64 s[0:1], s[94:95], 2
	v_readlane_b32 s2, v252, 25
	s_add_u32 s8, s2, s0
	v_readlane_b32 s0, v252, 26
	s_addc_u32 s9, s0, s1
	s_lshl_b32 s0, s94, 7
	v_ashrrev_i32_e32 v1, 6, v200
	s_ashr_i32 s1, s0, 31
	v_lshlrev_b32_e32 v0, 5, v1
	s_lshl_b64 s[0:1], s[0:1], 2
	v_readlane_b32 s2, v252, 27
	v_ashrrev_i32_e32 v203, 31, v0
	v_or_b32_e32 v202, v0, v157
	v_lshrrev_b32_e32 v0, 2, v200
	s_add_u32 s10, s2, s0
	v_readlane_b32 s0, v252, 28
	v_and_b32_e32 v0, 8, v0
	v_readlane_b32 s2, v253, 33
	s_addc_u32 s11, s0, s1
	v_cmp_eq_u32_e64 s[0:1], 0, v244
	v_lshl_add_u32 v195, v1, 2, s2
	v_lshlrev_b32_e32 v201, 8, v244
	v_lshlrev_b32_e32 v192, 1, v0
	v_readlane_b32 s20, v252, 47
	s_branch .LBB0_129

.LBB0_227:
	s_setprio 0
	s_mov_b64 s[0:1], 0
